# combo9: combo8 with the globally-last barrier leader no longer issuing (and waiting on) the unused generation atomic
# baseline (speedup 1.0000x reference)
; __device__ __forceinline__ unsigned xb_ld(unsigned* p)              { return __hip_atomic_load(p, __ATOMIC_RELAXED, __HIP_MEMORY_SCOPE_AGENT); }
; __device__ __forceinline__ unsigned xb_add(unsigned* p, unsigned v) { return __hip_atomic_fetch_add(p, v, __ATOMIC_RELAXED, __HIP_MEMORY_SCOPE_AGENT); }
; #define XB_SPIN(cond, bar) do { unsigned _sp = 0; while (cond) { __builtin_amdgcn_s_sleep(1); \
;     if ((++_sp & 255u) == 0u) { if (xb_ld(&(bar)[XB_TMO])) break; if (_sp > XB_SPIN_CAP) { atomicAdd(&(bar)[XB_TMO], 1u); break; } } } } while (0)
; __device__ __forceinline__ void xcd_barrier(const XcdBarrier& b) {
;     ...
;             asm volatile("s_waitcnt vmcnt(0)" ::: "memory");
;             const unsigned og = xb_add(&bar[XB_TOP], 1u);
;             const unsigned tg = og / nx;
;             if (og + 1u == (tg + 1u) * nx) xb_add(&bar[XB_TOPGEN], 1u);
;             else XB_SPIN(xb_ld(&bar[XB_TOPGEN]) == tg, bar);
.LBB0_109:
	s_or_b64 exec, exec, s[6:7]
	v_cvt_f32_u32_e32 v3, v0
	s_waitcnt vmcnt(0)
	v_readfirstlane_b32 s4, v2
	s_add_u32 s6, s68, 0xd6b0500
	s_addc_u32 s7, s69, 0
	s_add_u32 s100, s68, 0xd6b0400
	s_addc_u32 s101, s69, 0
	v_rcp_iflag_f32_e32 v3, v3
	v_add_u32_e32 v1, s4, v1
	v_add_u32_e32 v4, 1, v1
	s_mov_b64 s[8:9], 0
	v_mul_f32_e32 v2, 0x4f7ffffe, v3
	v_cvt_u32_f32_e32 v2, v2
	v_sub_u32_e32 v3, 0, v0
	v_mul_lo_u32 v3, v3, v2
	v_mul_hi_u32 v3, v2, v3
	v_add_u32_e32 v2, v2, v3
	v_mul_hi_u32 v2, v1, v2
	v_mul_lo_u32 v3, v2, v0
	v_sub_u32_e32 v1, v1, v3
	v_add_u32_e32 v5, 1, v2
	v_cmp_ge_u32_e32 vcc, v1, v0
	v_sub_u32_e32 v3, v1, v0
	s_nop 0
	v_cndmask_b32_e32 v2, v2, v5, vcc
	v_cndmask_b32_e32 v1, v1, v3, vcc
	v_add_u32_e32 v3, 1, v2
	v_cmp_ge_u32_e32 vcc, v1, v0
	s_nop 1
	v_cndmask_b32_e32 v2, v2, v3, vcc
	v_mul_lo_u32 v1, v0, v2
	v_add_u32_e32 v0, v1, v0
	v_mov_b32_e32 v210, v0
	v_cmp_ne_u32_e32 vcc, v4, v0
	v_mov_b64_e32 v[0:1], s[6:7]
	s_and_saveexec_b64 s[4:5], vcc
	s_cbranch_execz .LBB0_121
	v_mov_b32_e32 v0, 0
	global_load_dword v1, v0, s[100:101] sc1
	s_mov_b64 s[12:13], 0
	s_waitcnt vmcnt(0)
	v_cmp_lt_u32_e32 vcc, v1, v210
	s_and_saveexec_b64 s[10:11], vcc
	s_cbranch_execz .LBB0_120
	s_add_u32 s8, s68, 0xd6ad200
	s_addc_u32 s9, s69, 0
	s_mov_b32 s22, 1
	s_branch .LBB0_113
